# sc0 also on the one-shot f32 residual loads of the RES epilogue
# baseline (speedup 1.0000x reference)
; template <int EPI> ...
;     ...
;     } else if (EPI == EPI_RES) {
; #pragma unroll
;       for (int i = 0; i < 16; i++) {
;         const int rl = rbase + (i & 3) + 8 * (i >> 2);
;         const int row = m0 + rl;
;         float v0 = acc0[i], v1 = acc1[i];
;         xf[(size_t)row * 1024 + c0] = v0;
;         xf[(size_t)row * 1024 + c1] = v1;
;         outb[(size_t)row * 1024 + c0] = f2bf(v0);
;         outb[(size_t)row * 1024 + c1] = f2bf(v1);
;         float s = hsum32(v0 * v0 + v1 * v1);
;         if ((lane & 31) == 0) part[(size_t)row * 16 + nt * 2 + wn] = s;
; template <int EPI>
; __device__ __forceinline__ void gemm_phase(const Params& p, const u16* __restrict__ A, int lda, const u16* __restrict__ BT, int ldb,
;                            int K, int N, u16* __restrict__ outb, int ldo, int resid_in, int boff) {
;     ...
;     if (EPI == EPI_RES && !part_unit) {
;       const int cc0 = n0 + wn * 64 + (lane & 31);
;       float* xfq = p.out;
; #pragma unroll
;       for (int i = 0; i < 16; i++) {
;         const int row = m0 + wm * 64 + 4 * (lane >> 5) + (i & 3) + 8 * (i >> 2);
;         const float* ra = resid_in ? xrow(p, row) : (xfq + (size_t)row * 1024);
;         const float* rb = resid_in ? xrow(p, row + 32) : (xfq + (size_t)(row + 32) * 1024);
;         acc00[i] = ra[cc0]; acc01[i] = ra[cc0 + 32];
;         acc10[i] = rb[cc0]; acc11[i] = rb[cc0 + 32];
;       }
.Lgc_epi_res:
	s_lshl_b32 s11, s6, 8
	s_lshl_b32 s12, s4, 6
	s_add_u32 s11, s11, s12
	v_add_u32_e32 v238, s11, v248
	v_lshlrev_b32_e32 v243, 12, v238
	s_lshl_b32 s11, s7, 7
	v_lshl_add_u32 v239, v249, 2, s11
	v_lshlrev_b32_e32 v239, 2, v239
	v_add_u32_e32 v243, v243, v239
	v_add_u32_e32 v244, 0x10000, v243
	v_add_u32_e32 v245, 0x10000, v244
	v_add_u32_e32 v246, 0x10000, v245
	v_lshlrev_b32_e32 v247, 6, v238
	s_lshl_b32 s11, s7, 3
	v_add_u32_e32 v247, s11, v247
	s_lshl_b32 s11, s6, 8
	s_lshl_b32 s12, s4, 6
	s_add_u32 s11, s11, s12
	v_add_u32_e32 v238, s11, v248
	v_mul_lo_u32 v230, v238, s24
	s_lshl_b32 s11, s7, 7
	s_add_u32 s11, s11, s47
	v_and_b32_e32 v239, 1, v249
	v_lshrrev_b32_e32 v240, 1, v249
	v_lshlrev_b32_e32 v239, 4, v239
	v_lshl_add_u32 v239, v240, 3, v239
	v_add_u32_e32 v239, s11, v239
	v_lshlrev_b32_e32 v239, 1, v239
	v_add_u32_e32 v230, v230, v239
	s_lshl_b32 s11, s24, 4
	v_add_u32_e32 v231, s11, v230
	v_add_u32_e32 v232, s11, v231
	v_add_u32_e32 v233, s11, v232
	global_load_dwordx4 v[130:133], v243, s[48:49] sc0
	global_load_dwordx4 v[134:137], v243, s[48:49] offset:64 sc0
	global_load_dwordx4 v[138:141], v243, s[48:49] offset:128 sc0
	global_load_dwordx4 v[142:145], v243, s[48:49] offset:192 sc0
	global_load_dwordx4 v[146:149], v243, s[48:49] offset:256 sc0
	global_load_dwordx4 v[150:153], v243, s[48:49] offset:320 sc0
	global_load_dwordx4 v[154:157], v243, s[48:49] offset:384 sc0
	global_load_dwordx4 v[158:161], v243, s[48:49] offset:448 sc0
	global_load_dwordx4 v[162:165], v244, s[48:49] sc0
	global_load_dwordx4 v[166:169], v244, s[48:49] offset:64 sc0
	global_load_dwordx4 v[170:173], v244, s[48:49] offset:128 sc0
	global_load_dwordx4 v[174:177], v244, s[48:49] offset:192 sc0
	global_load_dwordx4 v[178:181], v244, s[48:49] offset:256 sc0
	global_load_dwordx4 v[182:185], v244, s[48:49] offset:320 sc0
	global_load_dwordx4 v[186:189], v244, s[48:49] offset:384 sc0
	global_load_dwordx4 v[190:193], v244, s[48:49] offset:448 sc0
	global_load_dwordx4 v[194:197], v245, s[48:49] sc0
	global_load_dwordx4 v[198:201], v245, s[48:49] offset:64 sc0
	global_load_dwordx4 v[202:205], v245, s[48:49] offset:128 sc0
	global_load_dwordx4 v[206:209], v245, s[48:49] offset:192 sc0
	global_load_dwordx4 v[210:213], v245, s[48:49] offset:256 sc0
	global_load_dwordx4 v[214:217], v245, s[48:49] offset:320 sc0
	global_load_dwordx4 v[218:221], v245, s[48:49] offset:384 sc0
	global_load_dwordx4 v[222:225], v245, s[48:49] offset:448 sc0
	s_waitcnt vmcnt(23)
	v_pk_add_f32 v[0:1], v[0:1], v[130:131]
	v_pk_add_f32 v[2:3], v[2:3], v[132:133]
	global_load_dwordx4 v[130:133], v246, s[48:49] sc0
	s_waitcnt vmcnt(23)
	v_pk_add_f32 v[4:5], v[4:5], v[134:135]
	v_pk_add_f32 v[6:7], v[6:7], v[136:137]
	global_load_dwordx4 v[134:137], v246, s[48:49] offset:64 sc0
	s_waitcnt vmcnt(23)
	v_pk_add_f32 v[8:9], v[8:9], v[138:139]
	v_pk_add_f32 v[10:11], v[10:11], v[140:141]
	global_load_dwordx4 v[138:141], v246, s[48:49] offset:128 sc0
	s_waitcnt vmcnt(23)
	v_pk_add_f32 v[12:13], v[12:13], v[142:143]
	v_pk_add_f32 v[14:15], v[14:15], v[144:145]
	global_load_dwordx4 v[142:145], v246, s[48:49] offset:192 sc0
	s_waitcnt vmcnt(23)
	v_pk_add_f32 v[16:17], v[16:17], v[146:147]
	v_pk_add_f32 v[18:19], v[18:19], v[148:149]
	global_load_dwordx4 v[146:149], v246, s[48:49] offset:256 sc0
	s_waitcnt vmcnt(23)
	v_pk_add_f32 v[20:21], v[20:21], v[150:151]
	v_pk_add_f32 v[22:23], v[22:23], v[152:153]
	global_load_dwordx4 v[150:153], v246, s[48:49] offset:320 sc0
	s_waitcnt vmcnt(23)
	v_pk_add_f32 v[24:25], v[24:25], v[154:155]
	v_pk_add_f32 v[26:27], v[26:27], v[156:157]
	global_load_dwordx4 v[154:157], v246, s[48:49] offset:384 sc0
	s_waitcnt vmcnt(23)
	v_pk_add_f32 v[28:29], v[28:29], v[158:159]
	v_pk_add_f32 v[30:31], v[30:31], v[160:161]
	global_load_dwordx4 v[158:161], v246, s[48:49] offset:448 sc0
	s_waitcnt vmcnt(23)
	v_pk_add_f32 v[32:33], v[32:33], v[162:163]
	v_pk_add_f32 v[34:35], v[34:35], v[164:165]
	s_waitcnt vmcnt(22)
	v_pk_add_f32 v[36:37], v[36:37], v[166:167]
	v_pk_add_f32 v[38:39], v[38:39], v[168:169]
	s_waitcnt vmcnt(21)
	v_pk_add_f32 v[40:41], v[40:41], v[170:171]
	v_pk_add_f32 v[42:43], v[42:43], v[172:173]
	s_waitcnt vmcnt(20)
	v_pk_add_f32 v[44:45], v[44:45], v[174:175]
	v_pk_add_f32 v[46:47], v[46:47], v[176:177]
	s_waitcnt vmcnt(19)
	v_pk_add_f32 v[48:49], v[48:49], v[178:179]
	v_pk_add_f32 v[50:51], v[50:51], v[180:181]
	s_waitcnt vmcnt(18)
	v_pk_add_f32 v[52:53], v[52:53], v[182:183]
	v_pk_add_f32 v[54:55], v[54:55], v[184:185]
	s_waitcnt vmcnt(17)
	v_pk_add_f32 v[56:57], v[56:57], v[186:187]
	v_pk_add_f32 v[58:59], v[58:59], v[188:189]
	s_waitcnt vmcnt(16)
	v_pk_add_f32 v[60:61], v[60:61], v[190:191]
	v_pk_add_f32 v[62:63], v[62:63], v[192:193]
	s_waitcnt vmcnt(15)
	v_pk_add_f32 v[64:65], v[64:65], v[194:195]
	v_pk_add_f32 v[66:67], v[66:67], v[196:197]
	s_waitcnt vmcnt(14)
	v_pk_add_f32 v[68:69], v[68:69], v[198:199]
	v_pk_add_f32 v[70:71], v[70:71], v[200:201]
	s_waitcnt vmcnt(13)
	v_pk_add_f32 v[72:73], v[72:73], v[202:203]
	v_pk_add_f32 v[74:75], v[74:75], v[204:205]
	s_waitcnt vmcnt(12)
	v_pk_add_f32 v[76:77], v[76:77], v[206:207]
	v_pk_add_f32 v[78:79], v[78:79], v[208:209]
	s_waitcnt vmcnt(11)
	v_pk_add_f32 v[80:81], v[80:81], v[210:211]
	v_pk_add_f32 v[82:83], v[82:83], v[212:213]
	s_waitcnt vmcnt(10)
	v_pk_add_f32 v[84:85], v[84:85], v[214:215]
	v_pk_add_f32 v[86:87], v[86:87], v[216:217]
	s_waitcnt vmcnt(9)
	v_pk_add_f32 v[88:89], v[88:89], v[218:219]
	v_pk_add_f32 v[90:91], v[90:91], v[220:221]
	s_waitcnt vmcnt(8)
	v_pk_add_f32 v[92:93], v[92:93], v[222:223]
	v_pk_add_f32 v[94:95], v[94:95], v[224:225]
	s_waitcnt vmcnt(7)
; template <int EPI> ...
;     ...
;     } else if (EPI == EPI_RES) {
; #pragma unroll
;       for (int i = 0; i < 16; i++) {
;         const int rl = rbase + (i & 3) + 8 * (i >> 2);
;         const int row = m0 + rl;
;         float v0 = acc0[i], v1 = acc1[i];
;         xf[(size_t)row * 1024 + c0] = v0;
;         xf[(size_t)row * 1024 + c1] = v1;
;         outb[(size_t)row * 1024 + c0] = f2bf(v0);
;         outb[(size_t)row * 1024 + c1] = f2bf(v1);
;         float s = hsum32(v0 * v0 + v1 * v1);
;         if ((lane & 31) == 0) part[(size_t)row * 16 + nt * 2 + wn] = s;
	v_pk_add_f32 v[96:97], v[96:97], v[130:131]
	v_pk_add_f32 v[98:99], v[98:99], v[132:133]
	s_waitcnt vmcnt(6)
	v_pk_add_f32 v[100:101], v[100:101], v[134:135]
	v_pk_add_f32 v[102:103], v[102:103], v[136:137]
	s_waitcnt vmcnt(5)
	v_pk_add_f32 v[104:105], v[104:105], v[138:139]
	v_pk_add_f32 v[106:107], v[106:107], v[140:141]
	s_waitcnt vmcnt(4)
	v_pk_add_f32 v[108:109], v[108:109], v[142:143]
	v_pk_add_f32 v[110:111], v[110:111], v[144:145]
	s_waitcnt vmcnt(3)
	v_pk_add_f32 v[112:113], v[112:113], v[146:147]
	v_pk_add_f32 v[114:115], v[114:115], v[148:149]
	s_waitcnt vmcnt(2)
	v_pk_add_f32 v[116:117], v[116:117], v[150:151]
	v_pk_add_f32 v[118:119], v[118:119], v[152:153]
	s_waitcnt vmcnt(1)
	v_pk_add_f32 v[120:121], v[120:121], v[154:155]
	v_pk_add_f32 v[122:123], v[122:123], v[156:157]
	s_waitcnt vmcnt(0)
	v_pk_add_f32 v[124:125], v[124:125], v[158:159]
	v_pk_add_f32 v[126:127], v[126:127], v[160:161]
	global_store_dwordx4 v243, v[0:3], s[94:95]
	v_mul_f32_e32 v234, v0, v0
	v_fmac_f32_e32 v234, v1, v1
	v_fmac_f32_e32 v234, v2, v2
	v_fmac_f32_e32 v234, v3, v3
	global_store_dwordx4 v243, v[4:7], s[94:95] offset:64
	v_fmac_f32_e32 v234, v4, v4
	v_fmac_f32_e32 v234, v5, v5
	v_fmac_f32_e32 v234, v6, v6
	v_fmac_f32_e32 v234, v7, v7
	global_store_dwordx4 v243, v[8:11], s[94:95] offset:128
	v_fmac_f32_e32 v234, v8, v8
	v_fmac_f32_e32 v234, v9, v9
	v_fmac_f32_e32 v234, v10, v10
	v_fmac_f32_e32 v234, v11, v11
	global_store_dwordx4 v243, v[12:15], s[94:95] offset:192
	v_fmac_f32_e32 v234, v12, v12
	v_fmac_f32_e32 v234, v13, v13
	v_fmac_f32_e32 v234, v14, v14
	v_fmac_f32_e32 v234, v15, v15
	global_store_dwordx4 v243, v[16:19], s[94:95] offset:256
	v_fmac_f32_e32 v234, v16, v16
	v_fmac_f32_e32 v234, v17, v17
	v_fmac_f32_e32 v234, v18, v18
	v_fmac_f32_e32 v234, v19, v19
	global_store_dwordx4 v243, v[20:23], s[94:95] offset:320
	v_fmac_f32_e32 v234, v20, v20
	v_fmac_f32_e32 v234, v21, v21
	v_fmac_f32_e32 v234, v22, v22
	v_fmac_f32_e32 v234, v23, v23
	global_store_dwordx4 v243, v[24:27], s[94:95] offset:384
	v_fmac_f32_e32 v234, v24, v24
	v_fmac_f32_e32 v234, v25, v25
	v_fmac_f32_e32 v234, v26, v26
	v_fmac_f32_e32 v234, v27, v27
	global_store_dwordx4 v243, v[28:31], s[94:95] offset:448
	v_fmac_f32_e32 v234, v28, v28
	v_fmac_f32_e32 v234, v29, v29
	v_fmac_f32_e32 v234, v30, v30
	v_fmac_f32_e32 v234, v31, v31
	global_store_dwordx4 v244, v[32:35], s[94:95]
	v_mul_f32_e32 v235, v32, v32
	v_fmac_f32_e32 v235, v33, v33
	v_fmac_f32_e32 v235, v34, v34
	v_fmac_f32_e32 v235, v35, v35
	global_store_dwordx4 v244, v[36:39], s[94:95] offset:64
	v_fmac_f32_e32 v235, v36, v36
	v_fmac_f32_e32 v235, v37, v37
	v_fmac_f32_e32 v235, v38, v38
	v_fmac_f32_e32 v235, v39, v39
	global_store_dwordx4 v244, v[40:43], s[94:95] offset:128
	v_fmac_f32_e32 v235, v40, v40
	v_fmac_f32_e32 v235, v41, v41
	v_fmac_f32_e32 v235, v42, v42
	v_fmac_f32_e32 v235, v43, v43
	global_store_dwordx4 v244, v[44:47], s[94:95] offset:192
	v_fmac_f32_e32 v235, v44, v44
	v_fmac_f32_e32 v235, v45, v45
	v_fmac_f32_e32 v235, v46, v46
	v_fmac_f32_e32 v235, v47, v47
	global_store_dwordx4 v244, v[48:51], s[94:95] offset:256
	v_fmac_f32_e32 v235, v48, v48
	v_fmac_f32_e32 v235, v49, v49
	v_fmac_f32_e32 v235, v50, v50
	v_fmac_f32_e32 v235, v51, v51
	global_store_dwordx4 v244, v[52:55], s[94:95] offset:320
	v_fmac_f32_e32 v235, v52, v52
	v_fmac_f32_e32 v235, v53, v53
	v_fmac_f32_e32 v235, v54, v54
	v_fmac_f32_e32 v235, v55, v55
	global_store_dwordx4 v244, v[56:59], s[94:95] offset:384
	v_fmac_f32_e32 v235, v56, v56
	v_fmac_f32_e32 v235, v57, v57
	v_fmac_f32_e32 v235, v58, v58
	v_fmac_f32_e32 v235, v59, v59
	global_store_dwordx4 v244, v[60:63], s[94:95] offset:448
	v_fmac_f32_e32 v235, v60, v60
	v_fmac_f32_e32 v235, v61, v61
	v_fmac_f32_e32 v235, v62, v62
	v_fmac_f32_e32 v235, v63, v63
	global_store_dwordx4 v245, v[64:67], s[94:95]
	v_mul_f32_e32 v236, v64, v64
	v_fmac_f32_e32 v236, v65, v65
	v_fmac_f32_e32 v236, v66, v66
	v_fmac_f32_e32 v236, v67, v67
	global_store_dwordx4 v245, v[68:71], s[94:95] offset:64
	v_fmac_f32_e32 v236, v68, v68
	v_fmac_f32_e32 v236, v69, v69
	v_fmac_f32_e32 v236, v70, v70
	v_fmac_f32_e32 v236, v71, v71
	global_store_dwordx4 v245, v[72:75], s[94:95] offset:128
	v_fmac_f32_e32 v236, v72, v72
	v_fmac_f32_e32 v236, v73, v73
	v_fmac_f32_e32 v236, v74, v74
	v_fmac_f32_e32 v236, v75, v75
	global_store_dwordx4 v245, v[76:79], s[94:95] offset:192
	v_fmac_f32_e32 v236, v76, v76
	v_fmac_f32_e32 v236, v77, v77
	v_fmac_f32_e32 v236, v78, v78
	v_fmac_f32_e32 v236, v79, v79
	global_store_dwordx4 v245, v[80:83], s[94:95] offset:256
	v_fmac_f32_e32 v236, v80, v80
	v_fmac_f32_e32 v236, v81, v81
	v_fmac_f32_e32 v236, v82, v82
	v_fmac_f32_e32 v236, v83, v83
	global_store_dwordx4 v245, v[84:87], s[94:95] offset:320
	v_fmac_f32_e32 v236, v84, v84
	v_fmac_f32_e32 v236, v85, v85
	v_fmac_f32_e32 v236, v86, v86
	v_fmac_f32_e32 v236, v87, v87
	global_store_dwordx4 v245, v[88:91], s[94:95] offset:384
	v_fmac_f32_e32 v236, v88, v88
	v_fmac_f32_e32 v236, v89, v89
	v_fmac_f32_e32 v236, v90, v90
	v_fmac_f32_e32 v236, v91, v91
	global_store_dwordx4 v245, v[92:95], s[94:95] offset:448
	v_fmac_f32_e32 v236, v92, v92
	v_fmac_f32_e32 v236, v93, v93
	v_fmac_f32_e32 v236, v94, v94
	v_fmac_f32_e32 v236, v95, v95
	global_store_dwordx4 v246, v[96:99], s[94:95]
	v_mul_f32_e32 v237, v96, v96
	v_fmac_f32_e32 v237, v97, v97
	v_fmac_f32_e32 v237, v98, v98
	v_fmac_f32_e32 v237, v99, v99
	global_store_dwordx4 v246, v[100:103], s[94:95] offset:64
	v_fmac_f32_e32 v237, v100, v100
	v_fmac_f32_e32 v237, v101, v101
	v_fmac_f32_e32 v237, v102, v102
	v_fmac_f32_e32 v237, v103, v103
	global_store_dwordx4 v246, v[104:107], s[94:95] offset:128
	v_fmac_f32_e32 v237, v104, v104
	v_fmac_f32_e32 v237, v105, v105
	v_fmac_f32_e32 v237, v106, v106
	v_fmac_f32_e32 v237, v107, v107
	global_store_dwordx4 v246, v[108:111], s[94:95] offset:192
	v_fmac_f32_e32 v237, v108, v108
	v_fmac_f32_e32 v237, v109, v109
	v_fmac_f32_e32 v237, v110, v110
	v_fmac_f32_e32 v237, v111, v111
	global_store_dwordx4 v246, v[112:115], s[94:95] offset:256
	v_fmac_f32_e32 v237, v112, v112
	v_fmac_f32_e32 v237, v113, v113
	v_fmac_f32_e32 v237, v114, v114
	v_fmac_f32_e32 v237, v115, v115
	global_store_dwordx4 v246, v[116:119], s[94:95] offset:320
	v_fmac_f32_e32 v237, v116, v116
	v_fmac_f32_e32 v237, v117, v117
	v_fmac_f32_e32 v237, v118, v118
	v_fmac_f32_e32 v237, v119, v119
	global_store_dwordx4 v246, v[120:123], s[94:95] offset:384
	v_fmac_f32_e32 v237, v120, v120
	v_fmac_f32_e32 v237, v121, v121
	v_fmac_f32_e32 v237, v122, v122
	v_fmac_f32_e32 v237, v123, v123
	global_store_dwordx4 v246, v[124:127], s[94:95] offset:448
	v_fmac_f32_e32 v237, v124, v124
	v_fmac_f32_e32 v237, v125, v125
	v_fmac_f32_e32 v237, v126, v126
	v_fmac_f32_e32 v237, v127, v127
	s_cmp_eq_u32 s101, 19
	s_cbranch_scc1 .Lgc_res_nobf
; template <int EPI> ...
;     ...
;     } else if (EPI == EPI_RES) {
; #pragma unroll
;       for (int i = 0; i < 16; i++) {
;         const int rl = rbase + (i & 3) + 8 * (i >> 2);
;         const int row = m0 + rl;
;         float v0 = acc0[i], v1 = acc1[i];
;         xf[(size_t)row * 1024 + c0] = v0;
;         xf[(size_t)row * 1024 + c1] = v1;
;         outb[(size_t)row * 1024 + c0] = f2bf(v0);
;         outb[(size_t)row * 1024 + c1] = f2bf(v1);
;         float s = hsum32(v0 * v0 + v1 * v1);
;         if ((lane & 31) == 0) part[(size_t)row * 16 + nt * 2 + wn] = s;
	v_cvt_pk_bf16_f32 v0, v0, v1
	v_cvt_pk_bf16_f32 v1, v2, v3
	v_cvt_pk_bf16_f32 v2, v4, v5
	v_cvt_pk_bf16_f32 v3, v6, v7
	s_nop 1
	v_permlane16_swap_b32_e32 v0, v2
	v_permlane16_swap_b32_e32 v1, v3
	global_store_dwordx4 v230, v[0:3], s[22:23]
	v_cvt_pk_bf16_f32 v8, v8, v9
	v_cvt_pk_bf16_f32 v9, v10, v11
	v_cvt_pk_bf16_f32 v10, v12, v13
	v_cvt_pk_bf16_f32 v11, v14, v15
	s_nop 1
	v_permlane16_swap_b32_e32 v8, v10
	v_permlane16_swap_b32_e32 v9, v11
	global_store_dwordx4 v230, v[8:11], s[22:23] offset:64
	v_cvt_pk_bf16_f32 v16, v16, v17
	v_cvt_pk_bf16_f32 v17, v18, v19
	v_cvt_pk_bf16_f32 v18, v20, v21
	v_cvt_pk_bf16_f32 v19, v22, v23
	s_nop 1
	v_permlane16_swap_b32_e32 v16, v18
	v_permlane16_swap_b32_e32 v17, v19
	global_store_dwordx4 v230, v[16:19], s[22:23] offset:128
	v_cvt_pk_bf16_f32 v24, v24, v25
	v_cvt_pk_bf16_f32 v25, v26, v27
	v_cvt_pk_bf16_f32 v26, v28, v29
	v_cvt_pk_bf16_f32 v27, v30, v31
	s_nop 1
	v_permlane16_swap_b32_e32 v24, v26
	v_permlane16_swap_b32_e32 v25, v27
	global_store_dwordx4 v230, v[24:27], s[22:23] offset:192
	v_cvt_pk_bf16_f32 v32, v32, v33
	v_cvt_pk_bf16_f32 v33, v34, v35
	v_cvt_pk_bf16_f32 v34, v36, v37
	v_cvt_pk_bf16_f32 v35, v38, v39
	s_nop 1
	v_permlane16_swap_b32_e32 v32, v34
	v_permlane16_swap_b32_e32 v33, v35
	global_store_dwordx4 v231, v[32:35], s[22:23]
	v_cvt_pk_bf16_f32 v40, v40, v41
	v_cvt_pk_bf16_f32 v41, v42, v43
	v_cvt_pk_bf16_f32 v42, v44, v45
	v_cvt_pk_bf16_f32 v43, v46, v47
	s_nop 1
	v_permlane16_swap_b32_e32 v40, v42
	v_permlane16_swap_b32_e32 v41, v43
	global_store_dwordx4 v231, v[40:43], s[22:23] offset:64
	v_cvt_pk_bf16_f32 v48, v48, v49
	v_cvt_pk_bf16_f32 v49, v50, v51
	v_cvt_pk_bf16_f32 v50, v52, v53
	v_cvt_pk_bf16_f32 v51, v54, v55
	s_nop 1
	v_permlane16_swap_b32_e32 v48, v50
	v_permlane16_swap_b32_e32 v49, v51
	global_store_dwordx4 v231, v[48:51], s[22:23] offset:128
	v_cvt_pk_bf16_f32 v56, v56, v57
	v_cvt_pk_bf16_f32 v57, v58, v59
	v_cvt_pk_bf16_f32 v58, v60, v61
	v_cvt_pk_bf16_f32 v59, v62, v63
	s_nop 1
	v_permlane16_swap_b32_e32 v56, v58
	v_permlane16_swap_b32_e32 v57, v59
	global_store_dwordx4 v231, v[56:59], s[22:23] offset:192
	v_cvt_pk_bf16_f32 v64, v64, v65
	v_cvt_pk_bf16_f32 v65, v66, v67
	v_cvt_pk_bf16_f32 v66, v68, v69
	v_cvt_pk_bf16_f32 v67, v70, v71
	s_nop 1
	v_permlane16_swap_b32_e32 v64, v66
	v_permlane16_swap_b32_e32 v65, v67
	global_store_dwordx4 v232, v[64:67], s[22:23]
	v_cvt_pk_bf16_f32 v72, v72, v73
	v_cvt_pk_bf16_f32 v73, v74, v75
	v_cvt_pk_bf16_f32 v74, v76, v77
	v_cvt_pk_bf16_f32 v75, v78, v79
	s_nop 1
	v_permlane16_swap_b32_e32 v72, v74
	v_permlane16_swap_b32_e32 v73, v75
	global_store_dwordx4 v232, v[72:75], s[22:23] offset:64
	v_cvt_pk_bf16_f32 v80, v80, v81
	v_cvt_pk_bf16_f32 v81, v82, v83
	v_cvt_pk_bf16_f32 v82, v84, v85
	v_cvt_pk_bf16_f32 v83, v86, v87
	s_nop 1
	v_permlane16_swap_b32_e32 v80, v82
	v_permlane16_swap_b32_e32 v81, v83
	global_store_dwordx4 v232, v[80:83], s[22:23] offset:128
	v_cvt_pk_bf16_f32 v88, v88, v89
	v_cvt_pk_bf16_f32 v89, v90, v91
	v_cvt_pk_bf16_f32 v90, v92, v93
	v_cvt_pk_bf16_f32 v91, v94, v95
	s_nop 1
	v_permlane16_swap_b32_e32 v88, v90
	v_permlane16_swap_b32_e32 v89, v91
	global_store_dwordx4 v232, v[88:91], s[22:23] offset:192
	v_cvt_pk_bf16_f32 v96, v96, v97
	v_cvt_pk_bf16_f32 v97, v98, v99
	v_cvt_pk_bf16_f32 v98, v100, v101
	v_cvt_pk_bf16_f32 v99, v102, v103
	s_nop 1
	v_permlane16_swap_b32_e32 v96, v98
	v_permlane16_swap_b32_e32 v97, v99
	global_store_dwordx4 v233, v[96:99], s[22:23]
	v_cvt_pk_bf16_f32 v104, v104, v105
	v_cvt_pk_bf16_f32 v105, v106, v107
	v_cvt_pk_bf16_f32 v106, v108, v109
	v_cvt_pk_bf16_f32 v107, v110, v111
	s_nop 1
	v_permlane16_swap_b32_e32 v104, v106
	v_permlane16_swap_b32_e32 v105, v107
	global_store_dwordx4 v233, v[104:107], s[22:23] offset:64
	v_cvt_pk_bf16_f32 v112, v112, v113
	v_cvt_pk_bf16_f32 v113, v114, v115
	v_cvt_pk_bf16_f32 v114, v116, v117
	v_cvt_pk_bf16_f32 v115, v118, v119
	s_nop 1
	v_permlane16_swap_b32_e32 v112, v114
	v_permlane16_swap_b32_e32 v113, v115
	global_store_dwordx4 v233, v[112:115], s[22:23] offset:128
	v_cvt_pk_bf16_f32 v120, v120, v121
	v_cvt_pk_bf16_f32 v121, v122, v123
	v_cvt_pk_bf16_f32 v122, v124, v125
	v_cvt_pk_bf16_f32 v123, v126, v127
	s_nop 1
	v_permlane16_swap_b32_e32 v120, v122
	v_permlane16_swap_b32_e32 v121, v123
	global_store_dwordx4 v233, v[120:123], s[22:23] offset:192
